# comb24 + attention main loops: the first four K-fragment reads of the QK^T block are issued at the loop top (before the DMA/address code) instead of at the block start
# speedup vs baseline: 1.0088x; 1.0003x over previous
; #define LAS __attribute__((address_space(3)))
; __device__ __forceinline__ unsigned cvt_pk(float lo, float hi) { unsigned r; asm volatile("v_cvt_pk_bf16_f32 %0, %1, %2" : "=v"(r) : "v"(lo), "v"(hi)); return r; }
; __device__ __forceinline__ void attn_unit(LAS unsigned char* lds, int b, int h, int q0, int kbeg, int ntiles, const bf16_t* Q, const bf16_t* K, const bf16_t* Vt, bf16_t* cat) {
;     ...
;         const LAS unsigned char* kb = lds + (buf ^ 1) * AK_BYTES + r32 * (KP * 2) + hi * 16;
;         f32x16 pn0, pn1;
; #pragma unroll
;         for (int r = 0; r < 16; ++r) { pn0[r] = 0.f; pn1[r] = 0.f; }
;         float ps = 0.f; u32x4 pw[4];
;         bf16x8 ka = *(const LAS bf16x8*)(kb), kbb = *(const LAS bf16x8*)(kb + 32 * (KP * 2));
; #pragma unroll
;         for (int ds = 0; ds < 12; ++ds) {
;             bf16x8 na = ka, nb = kbb;
;             if (ds < 11) { na = *(const LAS bf16x8*)(kb + (ds + 1) * 32); nb = *(const LAS bf16x8*)(kb + 32 * (KP * 2) + (ds + 1) * 32); }
;             pn0 = __builtin_amdgcn_mfma_f32_32x32x16_bf16(ka, qf[ds], pn0, 0, 0, 0);
;             pn1 = __builtin_amdgcn_mfma_f32_32x32x16_bf16(kbb, qf[ds], pn1, 0, 0, 0);
;             if (ds < 8) {
;                 float e[4];
; #pragma unroll
;                 for (int j = 0; j < 4; ++j) { const float v = ds < 4 ? pc0[4 * ds + j] : pc1[4 * (ds - 4) + j]; e[j] = __builtin_amdgcn_exp2f(v - mrun); }
;                 ps += (e[0] + e[1]) + (e[2] + e[3]);
;                 const unsigned w0 = cvt_pk(e[0], e[1]), w1 = cvt_pk(e[2], e[3]);
;                 if ((ds & 1) == 0) { pw[ds >> 1].x = w0; pw[ds >> 1].y = w1; } else { pw[ds >> 1].z = w0; pw[ds >> 1].w = w1; }
;             }
;             ka = na; kbb = nb;
;             __builtin_amdgcn_sched_barrier(0);
;         }
.LBB0_814:
	s_xor_b32 s6, s5, 1
	v_sub_f32_e32 v82, v82, v230
	v_exp_f32_e32 v197, v82
	v_sub_f32_e32 v82, v84, v230
	v_exp_f32_e32 v201, v82
	v_sub_f32_e32 v82, v85, v230
	v_exp_f32_e32 v233, v82
	v_sub_f32_e32 v82, v86, v230
	v_exp_f32_e32 v196, v82
	v_sub_f32_e32 v82, v87, v230
	s_waitcnt lgkmcnt(0)
	v_mfma_f32_32x32x16_bf16 v[98:113], v[240:243], v[174:177], 0
	v_exp_f32_e32 v198, v82
	v_sub_f32_e32 v82, v88, v230
	v_sub_f32_e32 v83, v83, v230
	v_exp_f32_e32 v200, v82
	v_sub_f32_e32 v82, v89, v230
	v_exp_f32_e32 v199, v83
	v_exp_f32_e32 v232, v82
	s_add_i32 s4, s4, 1
	v_add_f32_e32 v82, v196, v198
	v_add_f32_e32 v83, v197, v199
	v_add_f32_e32 v84, v200, v232
	v_add_f32_e32 v85, v201, v233
	s_waitcnt lgkmcnt(1)
	v_mfma_f32_32x32x16_bf16 v[114:129], v[114:117], v[174:177], 0
	v_add_f32_e64 v234, v82, v84
	v_add_f32_e64 v235, v83, v85
	v_cvt_pk_bf16_f32 v186, v197, v199
	v_cvt_pk_bf16_f32 v187, v201, v233
	v_add_f32_e32 v235, 0, v235
	v_mfma_f32_32x32x16_bf16 v[98:113], v[188:191], v[170:173], v[98:113]
	ds_read_b128 v[82:85], v236 offset:64
	ds_read_b128 v[86:89], v236 offset:12864
	v_add_f32_e32 v197, v234, v235
	v_cvt_pk_bf16_f32 v188, v196, v198
	v_cvt_pk_bf16_f32 v189, v200, v232
	s_waitcnt lgkmcnt(2)
	v_mfma_f32_32x32x16_bf16 v[114:129], v[192:195], v[170:173], v[114:129]
	v_sub_f32_e32 v90, v90, v230
	s_waitcnt lgkmcnt(1)
	v_mfma_f32_32x32x16_bf16 v[98:113], v[82:85], v[166:169], v[98:113]
	v_exp_f32_e32 v190, v90
	v_sub_f32_e32 v90, v91, v230
	v_exp_f32_e32 v192, v90
	v_sub_f32_e32 v90, v92, v230
	v_sub_f32_e32 v82, v93, v230
	v_exp_f32_e32 v191, v90
	v_exp_f32_e32 v193, v82
	ds_read_b128 v[82:85], v236 offset:96
	ds_read_b128 v[90:93], v236 offset:12896
	s_waitcnt lgkmcnt(2)
	v_mfma_f32_32x32x16_bf16 v[114:129], v[86:89], v[166:169], v[114:129]
	v_add_f32_e64 v194, v190, v192
	v_add_f32_e64 v195, v191, v193
	v_add_f32_e64 v198, v194, v194
	v_add_f32_e64 v199, v194, v195
	v_cvt_pk_bf16_f32 v190, v190, v192
	v_cvt_pk_bf16_f32 v191, v191, v193
	v_sub_f32_e32 v86, v94, v230
	s_waitcnt lgkmcnt(1)
	v_mfma_f32_32x32x16_bf16 v[98:113], v[82:85], v[162:165], v[98:113]
	v_exp_f32_e32 v94, v86
	v_sub_f32_e32 v86, v95, v230
	v_exp_f32_e32 v192, v86
	v_sub_f32_e32 v86, v96, v230
	v_sub_f32_e32 v82, v97, v230
	v_exp_f32_e32 v96, v86
	v_exp_f32_e32 v193, v82
	ds_read_b128 v[82:85], v236 offset:128
	ds_read_b128 v[86:89], v236 offset:12928
	v_add_f32_e32 v95, v94, v192
	v_cvt_pk_bf16_f32 v192, v94, v192
	v_add_f32_e32 v97, v96, v193
	s_waitcnt lgkmcnt(2)
	v_mfma_f32_32x32x16_bf16 v[114:129], v[90:93], v[162:165], v[114:129]
	v_cvt_pk_bf16_f32 v193, v96, v193
	v_sub_f32_e32 v66, v66, v230
	v_exp_f32_e32 v94, v66
	v_sub_f32_e32 v66, v67, v230
	v_exp_f32_e32 v96, v66
	v_sub_f32_e32 v66, v68, v230
	v_exp_f32_e32 v198, v66
	s_waitcnt lgkmcnt(1)
	v_mfma_f32_32x32x16_bf16 v[98:113], v[82:85], v[158:161], v[98:113]
	v_sub_f32_e32 v66, v69, v230
	v_exp_f32_e32 v196, v66
	ds_read_b128 v[66:69], v236 offset:160
	ds_read_b128 v[82:85], v236 offset:12960
	v_add_f32_e32 v90, v94, v96
	v_add_f32_e32 v91, v95, v97
	v_cvt_pk_bf16_f32 v194, v94, v96
	v_add_f32_e32 v92, v198, v196
	v_add_f32_e32 v93, v199, v197
	v_cvt_pk_bf16_f32 v195, v198, v196
	s_waitcnt lgkmcnt(2)
	v_mfma_f32_32x32x16_bf16 v[114:129], v[86:89], v[158:161], v[114:129]
	v_add_f32_e64 v90, v90, v92
	v_add_f32_e64 v91, v91, v93
	v_add_f32_e64 v86, v90, v90
	v_add_f32_e64 v87, v90, v91
	v_sub_f32_e32 v70, v70, v230
	v_exp_f32_e32 v88, v70
	v_sub_f32_e32 v70, v71, v230
	s_waitcnt lgkmcnt(1)
	v_mfma_f32_32x32x16_bf16 v[98:113], v[66:69], v[154:157], v[98:113]
	v_exp_f32_e32 v90, v70
	v_sub_f32_e32 v70, v72, v230
	v_sub_f32_e32 v66, v73, v230
	v_exp_f32_e32 v89, v70
	v_exp_f32_e32 v91, v66
	ds_read_b128 v[66:69], v236 offset:192
	ds_read_b128 v[70:73], v236 offset:12992
	v_cvt_pk_bf16_f32 v196, v88, v90
	s_waitcnt lgkmcnt(2)
	v_mfma_f32_32x32x16_bf16 v[114:129], v[82:85], v[154:157], v[114:129]
	v_add_f32_e64 v92, v88, v90
	v_add_f32_e64 v93, v89, v91
	v_cvt_pk_bf16_f32 v197, v89, v91
	v_add_f32_e32 v93, v92, v93
	v_add_f32_e32 v92, v92, v92
	v_sub_f32_e32 v74, v74, v230
	s_waitcnt lgkmcnt(1)
	v_mfma_f32_32x32x16_bf16 v[98:113], v[66:69], v[150:153], v[98:113]
	v_exp_f32_e32 v82, v74
	v_sub_f32_e32 v74, v75, v230
	v_exp_f32_e32 v84, v74
	v_sub_f32_e32 v74, v76, v230
	v_sub_f32_e32 v66, v77, v230
	v_exp_f32_e32 v86, v74
	v_exp_f32_e32 v88, v66
	ds_read_b128 v[66:69], v236 offset:224
	ds_read_b128 v[74:77], v236 offset:13024
	v_add_f32_e32 v83, v82, v84
	v_cvt_pk_bf16_f32 v198, v82, v84
	v_add_f32_e32 v85, v86, v88
	s_waitcnt lgkmcnt(2)
	v_mfma_f32_32x32x16_bf16 v[114:129], v[70:73], v[150:153], v[114:129]
	v_cvt_pk_bf16_f32 v199, v86, v88
	v_sub_f32_e32 v70, v78, v230
	v_exp_f32_e32 v82, v70
	v_sub_f32_e32 v70, v79, v230
	s_waitcnt lgkmcnt(1)
	v_mfma_f32_32x32x16_bf16 v[98:113], v[66:69], v[146:149], v[98:113]
	v_exp_f32_e32 v84, v70
	v_sub_f32_e32 v70, v80, v230
	v_sub_f32_e32 v66, v81, v230
	v_exp_f32_e32 v92, v70
	v_exp_f32_e32 v86, v66
	ds_read_b128 v[66:69], v236 offset:256
	ds_read_b128 v[70:73], v236 offset:13056
	v_add_f32_e32 v78, v82, v84
	v_add_f32_e32 v79, v83, v85
	s_waitcnt lgkmcnt(2)
	v_mfma_f32_32x32x16_bf16 v[114:129], v[74:77], v[146:149], v[114:129]
	v_add_f32_e64 v80, v92, v86
	v_add_f32_e64 v81, v93, v87
	v_cvt_pk_bf16_f32 v200, v82, v84
	v_cvt_pk_bf16_f32 v201, v92, v86
	v_add_f32_e64 v78, v78, v80
	v_add_f32_e64 v79, v79, v81
	v_add_f32_e32 v237, v78, v79
	s_waitcnt lgkmcnt(1)
; #define LAS __attribute__((address_space(3)))
; #define ALOADV(kt) do { vr[0] = *(const u32x4*)(Vg + (size_t)vd0 * NT + (kt) * 64 + vpart * 8); vr[1] = *(const u32x4*)(Vg + (size_t)(vd0 + 64) * NT + (kt) * 64 + vpart * 8); } while (0)
; __device__ __forceinline__ void attn_unit(LAS unsigned char* lds, int b, int h, int q0, int kbeg, int ntiles, const bf16_t* Q, const bf16_t* K, const bf16_t* Vt, bf16_t* cat) {
;     ...
;         const int buf = kt & 1;
;         if (kt + 2 < ntiles) ALOADK(kt + 2, buf);
;         if (kt + 1 < ntiles) ALOADV(kt + 1);
;         if (__any(mxc > mrun + 8.f)) {
;             const float mnew = fmaxf(mrun, mxc), alpha = __builtin_amdgcn_exp2f(mrun - mnew);
;             mrun = mnew; lrun *= alpha;
; #pragma unroll
;             for (int d = 0; d < 4; ++d)
; #pragma unroll
;                 for (int r = 0; r < 16; ++r) o[d][r] *= alpha;
;         }
;         const LAS unsigned char* kb = lds + (buf ^ 1) * AK_BYTES + r32 * (KP * 2) + hi * 16;
;         f32x16 pn0, pn1;
; #pragma unroll
;         for (int r = 0; r < 16; ++r) { pn0[r] = 0.f; pn1[r] = 0.f; }
;         float ps = 0.f; u32x4 pw[4];
;         bf16x8 ka = *(const LAS bf16x8*)(kb), kbb = *(const LAS bf16x8*)(kb + 32 * (KP * 2));
;     ...
;         const LAS unsigned char* vb = lds + 2 * AK_BYTES + buf * AV_BYTES + r32 * AV_PITCH + hi * 8;
; #pragma unroll
;         for (int d = 0; d < 4; ++d)
; #pragma unroll
;             for (int ks = 0; ks < 4; ++ks) {
;                 const s16x4 lo = *(const LAS s16x4*)(vb + d * 32 * AV_PITCH + ks * 32), hh = *(const LAS s16x4*)(vb + d * 32 * AV_PITCH + ks * 32 + 16);
;                 const bf16x8 vf = (bf16x8){lo[0], lo[1], lo[2], lo[3], hh[0], hh[1], hh[2], hh[3]};
;                 o[d] = __builtin_amdgcn_mfma_f32_32x32x16_bf16(vf, __builtin_bit_cast(bf16x8, pw[ks]), o[d], 0, 0, 0);
;             }
;         { float mx = fmaxf(pn0[0], pn1[0]);
; #pragma unroll
;           for (int r = 1; r < 16; ++r) mx = fmaxf(mx, fmaxf(pn0[r], pn1[r]));
;           mxc = fmaxf(mx, __shfl_xor(mx, 32)); }
;         if (kt + 1 < ntiles) ASTOREV(buf ^ 1);
;         asm volatile("s_waitcnt vmcnt(0)" ::: "memory");
;         __syncthreads();
	v_mfma_f32_32x32x16_bf16 v[98:113], v[66:69], v[142:145], v[98:113]
	ds_read_b128 v[66:69], v236 offset:288
	ds_read_b128 v[74:77], v236 offset:13088
	s_waitcnt lgkmcnt(2)
	v_mfma_f32_32x32x16_bf16 v[114:129], v[70:73], v[142:145], v[114:129]
	s_waitcnt lgkmcnt(1)
	v_mfma_f32_32x32x16_bf16 v[98:113], v[66:69], v[138:141], v[98:113]
	ds_read_b128 v[66:69], v236 offset:320
	ds_read_b128 v[70:73], v236 offset:13120
	s_waitcnt lgkmcnt(2)
	v_mfma_f32_32x32x16_bf16 v[114:129], v[74:77], v[138:141], v[114:129]
	s_waitcnt lgkmcnt(1)
	v_mfma_f32_32x32x16_bf16 v[98:113], v[66:69], v[134:137], v[98:113]
	ds_read_b128 v[66:69], v236 offset:352
	ds_read_b128 v[232:235], v236 offset:13152
	s_waitcnt lgkmcnt(2)
	v_mfma_f32_32x32x16_bf16 v[114:129], v[70:73], v[134:137], v[114:129]
	s_waitcnt lgkmcnt(1)
	v_mfma_f32_32x32x16_bf16 v[82:97], v[66:69], v[130:133], v[98:113]
	s_waitcnt lgkmcnt(0)
	v_mfma_f32_32x32x16_bf16 v[66:81], v[232:235], v[130:133], v[114:129]
	s_mulk_i32 s5, 0x4400
	v_add_u32_e32 v232, s5, v229
	v_add_u32_e32 v250, 0xc800, v232
	v_add_u32_e32 v251, 0xd800, v232
	v_add_u32_e32 v252, 0xe800, v232
	v_add_u32_e32 v253, 0xf800, v232
	s_mulk_i32 s6, 0x4400
	ds_read2_b64 v[98:101], v250 offset1:2
	ds_read2_b64 v[102:105], v251 offset0:32 offset1:34
	ds_read2_b64 v[106:109], v252 offset0:64 offset1:66
	ds_read2_b64 v[110:113], v253 offset0:96 offset1:98
	ds_read2_b64 v[114:117], v250 offset0:4 offset1:6
	ds_read2_b64 v[118:121], v251 offset0:36 offset1:38
	ds_read2_b64 v[122:125], v252 offset0:68 offset1:70
	ds_read2_b64 v[126:129], v253 offset0:100 offset1:102
	v_add_f32_e32 v202, v202, v237
	v_max3_f32 v254, v82, v66, v83
	v_max3_f32 v254, v254, v67, v84
	v_max3_f32 v254, v254, v68, v85
	v_max3_f32 v254, v254, v69, v86
	s_waitcnt lgkmcnt(7)
	v_mfma_f32_32x32x16_bf16 v[50:65], v[98:101], v[186:189], v[50:65]
	ds_read2_b64 v[98:101], v250 offset0:8 offset1:10
	v_max3_f32 v254, v254, v70, v87
	v_max3_f32 v254, v254, v71, v88
	s_waitcnt lgkmcnt(7)
	v_mfma_f32_32x32x16_bf16 v[34:49], v[102:105], v[186:189], v[34:49]
	ds_read2_b64 v[102:105], v251 offset0:40 offset1:42
	v_max3_f32 v254, v254, v72, v89
	v_max3_f32 v254, v254, v73, v90
	s_waitcnt lgkmcnt(7)
	v_mfma_f32_32x32x16_bf16 v[18:33], v[106:109], v[186:189], v[18:33]
	ds_read2_b64 v[106:109], v252 offset0:72 offset1:74
	v_max3_f32 v254, v254, v74, v91
	v_max3_f32 v254, v254, v75, v92
	s_waitcnt lgkmcnt(7)
	v_mfma_f32_32x32x16_bf16 v[2:17], v[110:113], v[186:189], v[2:17]
	ds_read2_b64 v[110:113], v253 offset0:104 offset1:106
	v_max3_f32 v254, v254, v76, v93
	v_max3_f32 v254, v254, v77, v94
	s_waitcnt lgkmcnt(7)
	v_mfma_f32_32x32x16_bf16 v[50:65], v[114:117], v[190:193], v[50:65]
	ds_read2_b64 v[114:117], v250 offset0:12 offset1:14
	v_max3_f32 v254, v254, v78, v95
	v_max3_f32 v254, v254, v79, v96
	s_waitcnt lgkmcnt(7)
	v_mfma_f32_32x32x16_bf16 v[34:49], v[118:121], v[190:193], v[34:49]
	ds_read2_b64 v[118:121], v251 offset0:44 offset1:46
	v_max3_f32 v254, v254, v80, v97
	v_max_f32_e32 v254, v254, v81
	s_waitcnt lgkmcnt(7)
	v_mfma_f32_32x32x16_bf16 v[18:33], v[122:125], v[190:193], v[18:33]
	ds_read2_b64 v[122:125], v252 offset0:76 offset1:78
	v_lshl_add_u64 v[212:213], v[212:213], 0, s[60:61]
	v_lshl_add_u64 v[214:215], v[214:215], 0, s[60:61]
	s_waitcnt lgkmcnt(7)
	v_mfma_f32_32x32x16_bf16 v[2:17], v[126:129], v[190:193], v[2:17]
	ds_read2_b64 v[126:129], v253 offset0:108 offset1:110
	v_lshl_add_u64 v[216:217], v[216:217], 0, s[60:61]
	v_lshl_add_u64 v[218:219], v[218:219], 0, s[60:61]
	v_lshl_add_u64 v[220:221], v[220:221], 0, s[66:67]
	ds_bpermute_b32 v255, v207, v254
	s_waitcnt lgkmcnt(8)
	v_mfma_f32_32x32x16_bf16 v[50:65], v[98:101], v[194:197], v[50:65]
	s_waitcnt lgkmcnt(7)
	v_mfma_f32_32x32x16_bf16 v[34:49], v[102:105], v[194:197], v[34:49]
	s_waitcnt lgkmcnt(6)
	v_mfma_f32_32x32x16_bf16 v[18:33], v[106:109], v[194:197], v[18:33]
	s_waitcnt lgkmcnt(5)
	v_mfma_f32_32x32x16_bf16 v[2:17], v[110:113], v[194:197], v[2:17]
	s_waitcnt lgkmcnt(0)
	v_max_f32_e32 v255, v255, v255
	v_max_f32_e32 v98, v254, v255
	v_add_u32_e32 v255, s6, v231
	v_add_u32_e32 v238, 0xc800, v255
	v_add_u32_e32 v255, 0xea00, v255
	s_cmp_lg_u32 s4, 34
	s_waitcnt vmcnt(0)
	ds_write2_b64 v238, v[178:179], v[180:181] offset1:1
	ds_write2_b64 v255, v[182:183], v[184:185] offset1:1
	s_waitcnt vmcnt(0)
	s_waitcnt lgkmcnt(0)
	s_barrier
	v_mfma_f32_32x32x16_bf16 v[50:65], v[114:117], v[198:201], v[50:65]
	v_mfma_f32_32x32x16_bf16 v[34:49], v[118:121], v[198:201], v[34:49]
	v_mfma_f32_32x32x16_bf16 v[18:33], v[122:125], v[198:201], v[18:33]
	v_mfma_f32_32x32x16_bf16 v[2:17], v[126:129], v[198:201], v[2:17]
	s_cbranch_scc0 .LBB0_819
.LBB0_815:
	s_and_b32 s5, s4, 1
	s_xor_b32 s98, s5, 1
	s_mul_i32 s98, s98, 0x6400
	v_add_u32_e32 v236, s98, v228
	ds_read_b128 v[240:243], v236
	ds_read_b128 v[188:191], v236 offset:32
	ds_read_b128 v[114:117], v236 offset:12800
	ds_read_b128 v[192:195], v236 offset:12832
	s_mul_i32 s6, s5, 0x6400
	s_add_i32 s6, s6, 0
	s_add_i32 s7, s6, s68
	v_lshl_add_u64 v[100:101], s[30:31], 0, v[212:213]
	s_mov_b32 m0, s7
	s_and_b64 vcc, exec, s[2:3]
	global_load_lds_dwordx4 v[100:101], off
	v_lshl_add_u64 v[100:101], s[30:31], 0, v[214:215]
	s_add_i32 m0, s7, 0x2000
	s_nop 0
	global_load_lds_dwordx4 v[100:101], off
	v_lshl_add_u64 v[100:101], s[30:31], 0, v[216:217]
	s_add_i32 m0, s7, 0x4000
	s_nop 0
	global_load_lds_dwordx4 v[100:101], off
	s_cbranch_vccnz .LBB0_817
	s_add_i32 m0, s6, 0x6000
	v_lshl_add_u64 v[100:101], s[30:31], 0, v[218:219]
	global_load_lds_dwordx4 v[100:101], off

; #define LAS __attribute__((address_space(3)))
; __device__ __forceinline__ unsigned cvt_pk(float lo, float hi) { unsigned r; asm volatile("v_cvt_pk_bf16_f32 %0, %1, %2" : "=v"(r) : "v"(lo), "v"(hi)); return r; }
; __device__ __forceinline__ void attn_unit(LAS unsigned char* lds, int b, int h, int q0, int kbeg, int ntiles, const bf16_t* Q, const bf16_t* K, const bf16_t* Vt, bf16_t* cat) {
;     ...
;         const LAS unsigned char* kb = lds + (buf ^ 1) * AK_BYTES + r32 * (KP * 2) + hi * 16;
;         f32x16 pn0, pn1;
; #pragma unroll
;         for (int r = 0; r < 16; ++r) { pn0[r] = 0.f; pn1[r] = 0.f; }
;         float ps = 0.f; u32x4 pw[4];
;         bf16x8 ka = *(const LAS bf16x8*)(kb), kbb = *(const LAS bf16x8*)(kb + 32 * (KP * 2));
; #pragma unroll
;         for (int ds = 0; ds < 12; ++ds) {
;             bf16x8 na = ka, nb = kbb;
;             if (ds < 11) { na = *(const LAS bf16x8*)(kb + (ds + 1) * 32); nb = *(const LAS bf16x8*)(kb + 32 * (KP * 2) + (ds + 1) * 32); }
;             pn0 = __builtin_amdgcn_mfma_f32_32x32x16_bf16(ka, qf[ds], pn0, 0, 0, 0);
;             pn1 = __builtin_amdgcn_mfma_f32_32x32x16_bf16(kbb, qf[ds], pn1, 0, 0, 0);
;             if (ds < 8) {
;                 float e[4];
; #pragma unroll
;                 for (int j = 0; j < 4; ++j) { const float v = ds < 4 ? pc0[4 * ds + j] : pc1[4 * (ds - 4) + j]; e[j] = __builtin_amdgcn_exp2f(v - mrun); }
;                 ps += (e[0] + e[1]) + (e[2] + e[3]);
;                 const unsigned w0 = cvt_pk(e[0], e[1]), w1 = cvt_pk(e[2], e[3]);
;                 if ((ds & 1) == 0) { pw[ds >> 1].x = w0; pw[ds >> 1].y = w1; } else { pw[ds >> 1].z = w0; pw[ds >> 1].w = w1; }
;             }
;             ka = na; kbb = nb;
;             __builtin_amdgcn_sched_barrier(0);
;         }
.LBB0_1840:
	s_xor_b32 s6, s5, 1
	v_sub_f32_e32 v82, v82, v231
	v_exp_f32_e32 v197, v82
	v_sub_f32_e32 v82, v84, v231
	v_exp_f32_e32 v201, v82
	v_sub_f32_e32 v82, v85, v231
	v_exp_f32_e32 v235, v82
	v_sub_f32_e32 v82, v86, v231
	v_exp_f32_e32 v196, v82
	v_sub_f32_e32 v82, v87, v231
	s_waitcnt lgkmcnt(0)
	v_mfma_f32_32x32x16_bf16 v[98:113], v[240:243], v[174:177], 0
	v_exp_f32_e32 v198, v82
	v_sub_f32_e32 v82, v88, v231
	v_sub_f32_e32 v83, v83, v231
	v_exp_f32_e32 v200, v82
	v_sub_f32_e32 v82, v89, v231
	v_exp_f32_e32 v199, v83
	v_exp_f32_e32 v234, v82
	s_add_i32 s4, s4, 1
	v_add_f32_e32 v82, v196, v198
	v_add_f32_e32 v83, v197, v199
	v_add_f32_e32 v84, v200, v234
	v_add_f32_e32 v85, v201, v235
	s_waitcnt lgkmcnt(1)
	v_mfma_f32_32x32x16_bf16 v[114:129], v[114:117], v[174:177], 0
	v_add_f32_e64 v236, v82, v84
	v_add_f32_e64 v237, v83, v85
	v_cvt_pk_bf16_f32 v186, v197, v199
	v_cvt_pk_bf16_f32 v187, v201, v235
	v_add_f32_e32 v237, 0, v237
	v_mfma_f32_32x32x16_bf16 v[98:113], v[188:191], v[170:173], v[98:113]
	ds_read_b128 v[82:85], v233 offset:64
	ds_read_b128 v[86:89], v233 offset:12864
	v_add_f32_e32 v197, v236, v237
	v_cvt_pk_bf16_f32 v188, v196, v198
	v_cvt_pk_bf16_f32 v189, v200, v234
	s_waitcnt lgkmcnt(2)
	v_mfma_f32_32x32x16_bf16 v[114:129], v[192:195], v[170:173], v[114:129]
	v_sub_f32_e32 v90, v90, v231
	s_waitcnt lgkmcnt(1)
	v_mfma_f32_32x32x16_bf16 v[98:113], v[82:85], v[166:169], v[98:113]
	v_exp_f32_e32 v190, v90
	v_sub_f32_e32 v90, v91, v231
	v_exp_f32_e32 v192, v90
	v_sub_f32_e32 v90, v92, v231
	v_sub_f32_e32 v82, v93, v231
	v_exp_f32_e32 v191, v90
	v_exp_f32_e32 v193, v82
	ds_read_b128 v[82:85], v233 offset:96
	ds_read_b128 v[90:93], v233 offset:12896
	s_waitcnt lgkmcnt(2)
	v_mfma_f32_32x32x16_bf16 v[114:129], v[86:89], v[166:169], v[114:129]
	v_add_f32_e64 v194, v190, v192
	v_add_f32_e64 v195, v191, v193
	v_add_f32_e64 v198, v194, v194
	v_add_f32_e64 v199, v194, v195
	v_cvt_pk_bf16_f32 v190, v190, v192
	v_cvt_pk_bf16_f32 v191, v191, v193
	v_sub_f32_e32 v86, v94, v231
	s_waitcnt lgkmcnt(1)
	v_mfma_f32_32x32x16_bf16 v[98:113], v[82:85], v[162:165], v[98:113]
	v_exp_f32_e32 v94, v86
	v_sub_f32_e32 v86, v95, v231
	v_exp_f32_e32 v192, v86
	v_sub_f32_e32 v86, v96, v231
	v_sub_f32_e32 v82, v97, v231
	v_exp_f32_e32 v96, v86
	v_exp_f32_e32 v193, v82
	ds_read_b128 v[82:85], v233 offset:128
	ds_read_b128 v[86:89], v233 offset:12928
	v_add_f32_e32 v95, v94, v192
	v_cvt_pk_bf16_f32 v192, v94, v192
	v_add_f32_e32 v97, v96, v193
	s_waitcnt lgkmcnt(2)
	v_mfma_f32_32x32x16_bf16 v[114:129], v[90:93], v[162:165], v[114:129]
	v_cvt_pk_bf16_f32 v193, v96, v193
	v_sub_f32_e32 v66, v66, v231
	v_exp_f32_e32 v94, v66
	v_sub_f32_e32 v66, v67, v231
	v_exp_f32_e32 v96, v66
	v_sub_f32_e32 v66, v68, v231
	v_exp_f32_e32 v198, v66
	s_waitcnt lgkmcnt(1)
	v_mfma_f32_32x32x16_bf16 v[98:113], v[82:85], v[158:161], v[98:113]
	v_sub_f32_e32 v66, v69, v231
	v_exp_f32_e32 v196, v66
	ds_read_b128 v[66:69], v233 offset:160
	ds_read_b128 v[82:85], v233 offset:12960
	v_add_f32_e32 v90, v94, v96
	v_add_f32_e32 v91, v95, v97
	v_cvt_pk_bf16_f32 v194, v94, v96
	v_add_f32_e32 v92, v198, v196
	v_add_f32_e32 v93, v199, v197
	v_cvt_pk_bf16_f32 v195, v198, v196
	s_waitcnt lgkmcnt(2)
	v_mfma_f32_32x32x16_bf16 v[114:129], v[86:89], v[158:161], v[114:129]
	v_add_f32_e64 v90, v90, v92
	v_add_f32_e64 v91, v91, v93
	v_add_f32_e64 v86, v90, v90
	v_add_f32_e64 v87, v90, v91
	v_sub_f32_e32 v70, v70, v231
	v_exp_f32_e32 v88, v70
	v_sub_f32_e32 v70, v71, v231
	s_waitcnt lgkmcnt(1)
	v_mfma_f32_32x32x16_bf16 v[98:113], v[66:69], v[154:157], v[98:113]
	v_exp_f32_e32 v90, v70
	v_sub_f32_e32 v70, v72, v231
	v_sub_f32_e32 v66, v73, v231
	v_exp_f32_e32 v89, v70
	v_exp_f32_e32 v91, v66
	ds_read_b128 v[66:69], v233 offset:192
	ds_read_b128 v[70:73], v233 offset:12992
	v_cvt_pk_bf16_f32 v196, v88, v90
	s_waitcnt lgkmcnt(2)
	v_mfma_f32_32x32x16_bf16 v[114:129], v[82:85], v[154:157], v[114:129]
	v_add_f32_e64 v92, v88, v90
	v_add_f32_e64 v93, v89, v91
	v_cvt_pk_bf16_f32 v197, v89, v91
	v_add_f32_e32 v93, v92, v93
	v_add_f32_e32 v92, v92, v92
	v_sub_f32_e32 v74, v74, v231
	s_waitcnt lgkmcnt(1)
	v_mfma_f32_32x32x16_bf16 v[98:113], v[66:69], v[150:153], v[98:113]
	v_exp_f32_e32 v82, v74
	v_sub_f32_e32 v74, v75, v231
	v_exp_f32_e32 v84, v74
	v_sub_f32_e32 v74, v76, v231
	v_sub_f32_e32 v66, v77, v231
	v_exp_f32_e32 v86, v74
	v_exp_f32_e32 v88, v66
	ds_read_b128 v[66:69], v233 offset:224
	ds_read_b128 v[74:77], v233 offset:13024
	v_add_f32_e32 v83, v82, v84
	v_cvt_pk_bf16_f32 v198, v82, v84
	v_add_f32_e32 v85, v86, v88
	s_waitcnt lgkmcnt(2)
	v_mfma_f32_32x32x16_bf16 v[114:129], v[70:73], v[150:153], v[114:129]
	v_cvt_pk_bf16_f32 v199, v86, v88
	v_sub_f32_e32 v70, v78, v231
	v_exp_f32_e32 v82, v70
	v_sub_f32_e32 v70, v79, v231
	s_waitcnt lgkmcnt(1)
	v_mfma_f32_32x32x16_bf16 v[98:113], v[66:69], v[146:149], v[98:113]
	v_exp_f32_e32 v84, v70
	v_sub_f32_e32 v70, v80, v231
	v_sub_f32_e32 v66, v81, v231
	v_exp_f32_e32 v92, v70
	v_exp_f32_e32 v86, v66
	ds_read_b128 v[66:69], v233 offset:256
	ds_read_b128 v[70:73], v233 offset:13056
	v_add_f32_e32 v78, v82, v84
	v_add_f32_e32 v79, v83, v85
	s_waitcnt lgkmcnt(2)
	v_mfma_f32_32x32x16_bf16 v[114:129], v[74:77], v[146:149], v[114:129]
	v_add_f32_e64 v80, v92, v86
	v_add_f32_e64 v81, v93, v87
	v_cvt_pk_bf16_f32 v200, v82, v84
	v_cvt_pk_bf16_f32 v201, v92, v86
	v_add_f32_e64 v78, v78, v80
	v_add_f32_e64 v79, v79, v81
	v_add_f32_e32 v238, v78, v79
	s_waitcnt lgkmcnt(1)
; #define LAS __attribute__((address_space(3)))
; #define ALOADV(kt) do { vr[0] = *(const u32x4*)(Vg + (size_t)vd0 * NT + (kt) * 64 + vpart * 8); vr[1] = *(const u32x4*)(Vg + (size_t)(vd0 + 64) * NT + (kt) * 64 + vpart * 8); } while (0)
; __device__ __forceinline__ void attn_unit(LAS unsigned char* lds, int b, int h, int q0, int kbeg, int ntiles, const bf16_t* Q, const bf16_t* K, const bf16_t* Vt, bf16_t* cat) {
;     ...
;         const int buf = kt & 1;
;         if (kt + 2 < ntiles) ALOADK(kt + 2, buf);
;         if (kt + 1 < ntiles) ALOADV(kt + 1);
;         if (__any(mxc > mrun + 8.f)) {
;             const float mnew = fmaxf(mrun, mxc), alpha = __builtin_amdgcn_exp2f(mrun - mnew);
;             mrun = mnew; lrun *= alpha;
; #pragma unroll
;             for (int d = 0; d < 4; ++d)
; #pragma unroll
;                 for (int r = 0; r < 16; ++r) o[d][r] *= alpha;
;         }
;         const LAS unsigned char* kb = lds + (buf ^ 1) * AK_BYTES + r32 * (KP * 2) + hi * 16;
;         f32x16 pn0, pn1;
; #pragma unroll
;         for (int r = 0; r < 16; ++r) { pn0[r] = 0.f; pn1[r] = 0.f; }
;         float ps = 0.f; u32x4 pw[4];
;         bf16x8 ka = *(const LAS bf16x8*)(kb), kbb = *(const LAS bf16x8*)(kb + 32 * (KP * 2));
;     ...
;         const LAS unsigned char* vb = lds + 2 * AK_BYTES + buf * AV_BYTES + r32 * AV_PITCH + hi * 8;
; #pragma unroll
;         for (int d = 0; d < 4; ++d)
; #pragma unroll
;             for (int ks = 0; ks < 4; ++ks) {
;                 const s16x4 lo = *(const LAS s16x4*)(vb + d * 32 * AV_PITCH + ks * 32), hh = *(const LAS s16x4*)(vb + d * 32 * AV_PITCH + ks * 32 + 16);
;                 const bf16x8 vf = (bf16x8){lo[0], lo[1], lo[2], lo[3], hh[0], hh[1], hh[2], hh[3]};
;                 o[d] = __builtin_amdgcn_mfma_f32_32x32x16_bf16(vf, __builtin_bit_cast(bf16x8, pw[ks]), o[d], 0, 0, 0);
;             }
;         { float mx = fmaxf(pn0[0], pn1[0]);
; #pragma unroll
;           for (int r = 1; r < 16; ++r) mx = fmaxf(mx, fmaxf(pn0[r], pn1[r]));
;           mxc = fmaxf(mx, __shfl_xor(mx, 32)); }
;         if (kt + 1 < ntiles) ASTOREV(buf ^ 1);
;         asm volatile("s_waitcnt vmcnt(0)" ::: "memory");
;         __syncthreads();
	v_mfma_f32_32x32x16_bf16 v[98:113], v[66:69], v[142:145], v[98:113]
	ds_read_b128 v[66:69], v233 offset:288
	ds_read_b128 v[74:77], v233 offset:13088
	s_waitcnt lgkmcnt(2)
	v_mfma_f32_32x32x16_bf16 v[114:129], v[70:73], v[142:145], v[114:129]
	s_waitcnt lgkmcnt(1)
	v_mfma_f32_32x32x16_bf16 v[98:113], v[66:69], v[138:141], v[98:113]
	ds_read_b128 v[66:69], v233 offset:320
	ds_read_b128 v[70:73], v233 offset:13120
	s_waitcnt lgkmcnt(2)
	v_mfma_f32_32x32x16_bf16 v[114:129], v[74:77], v[138:141], v[114:129]
	s_waitcnt lgkmcnt(1)
	v_mfma_f32_32x32x16_bf16 v[98:113], v[66:69], v[134:137], v[98:113]
	ds_read_b128 v[66:69], v233 offset:352
	ds_read_b128 v[234:237], v233 offset:13152
	s_waitcnt lgkmcnt(2)
	v_mfma_f32_32x32x16_bf16 v[114:129], v[70:73], v[134:137], v[114:129]
	s_waitcnt lgkmcnt(1)
	v_mfma_f32_32x32x16_bf16 v[82:97], v[66:69], v[130:133], v[98:113]
	s_waitcnt lgkmcnt(0)
	v_mfma_f32_32x32x16_bf16 v[66:81], v[234:237], v[130:133], v[114:129]
	s_mulk_i32 s5, 0x4400
	v_add_u32_e32 v233, s5, v230
	v_add_u32_e32 v250, 0xc800, v233
	v_add_u32_e32 v251, 0xd800, v233
	v_add_u32_e32 v252, 0xe800, v233
	v_add_u32_e32 v253, 0xf800, v233
	s_mulk_i32 s6, 0x4400
	ds_read2_b64 v[98:101], v250 offset1:2
	ds_read2_b64 v[102:105], v251 offset0:32 offset1:34
	ds_read2_b64 v[106:109], v252 offset0:64 offset1:66
	ds_read2_b64 v[110:113], v253 offset0:96 offset1:98
	ds_read2_b64 v[114:117], v250 offset0:4 offset1:6
	ds_read2_b64 v[118:121], v251 offset0:36 offset1:38
	ds_read2_b64 v[122:125], v252 offset0:68 offset1:70
	ds_read2_b64 v[126:129], v253 offset0:100 offset1:102
	v_add_f32_e32 v202, v202, v238
	v_max3_f32 v254, v82, v66, v83
	v_max3_f32 v254, v254, v67, v84
	v_max3_f32 v254, v254, v68, v85
	v_max3_f32 v254, v254, v69, v86
	s_waitcnt lgkmcnt(7)
	v_mfma_f32_32x32x16_bf16 v[50:65], v[98:101], v[186:189], v[50:65]
	ds_read2_b64 v[98:101], v250 offset0:8 offset1:10
	v_max3_f32 v254, v254, v70, v87
	v_max3_f32 v254, v254, v71, v88
	s_waitcnt lgkmcnt(7)
	v_mfma_f32_32x32x16_bf16 v[34:49], v[102:105], v[186:189], v[34:49]
	ds_read2_b64 v[102:105], v251 offset0:40 offset1:42
	v_max3_f32 v254, v254, v72, v89
	v_max3_f32 v254, v254, v73, v90
	s_waitcnt lgkmcnt(7)
	v_mfma_f32_32x32x16_bf16 v[18:33], v[106:109], v[186:189], v[18:33]
	ds_read2_b64 v[106:109], v252 offset0:72 offset1:74
	v_max3_f32 v254, v254, v74, v91
	v_max3_f32 v254, v254, v75, v92
	s_waitcnt lgkmcnt(7)
	v_mfma_f32_32x32x16_bf16 v[2:17], v[110:113], v[186:189], v[2:17]
	ds_read2_b64 v[110:113], v253 offset0:104 offset1:106
	v_max3_f32 v254, v254, v76, v93
	v_max3_f32 v254, v254, v77, v94
	s_waitcnt lgkmcnt(7)
	v_mfma_f32_32x32x16_bf16 v[50:65], v[114:117], v[190:193], v[50:65]
	ds_read2_b64 v[114:117], v250 offset0:12 offset1:14
	v_max3_f32 v254, v254, v78, v95
	v_max3_f32 v254, v254, v79, v96
	s_waitcnt lgkmcnt(7)
	v_mfma_f32_32x32x16_bf16 v[34:49], v[118:121], v[190:193], v[34:49]
	ds_read2_b64 v[118:121], v251 offset0:44 offset1:46
	v_max3_f32 v254, v254, v80, v97
	v_max_f32_e32 v254, v254, v81
	s_waitcnt lgkmcnt(7)
	v_mfma_f32_32x32x16_bf16 v[18:33], v[122:125], v[190:193], v[18:33]
	ds_read2_b64 v[122:125], v252 offset0:76 offset1:78
	v_lshl_add_u64 v[214:215], v[214:215], 0, s[38:39]
	v_lshl_add_u64 v[216:217], v[216:217], 0, s[38:39]
	s_waitcnt lgkmcnt(7)
	v_mfma_f32_32x32x16_bf16 v[2:17], v[126:129], v[190:193], v[2:17]
	ds_read2_b64 v[126:129], v253 offset0:108 offset1:110
	v_lshl_add_u64 v[218:219], v[218:219], 0, s[38:39]
	v_lshl_add_u64 v[220:221], v[220:221], 0, s[38:39]
	v_lshl_add_u64 v[222:223], v[222:223], 0, s[40:41]
	ds_bpermute_b32 v255, v209, v254
	s_waitcnt lgkmcnt(8)
	v_mfma_f32_32x32x16_bf16 v[50:65], v[98:101], v[194:197], v[50:65]
	s_waitcnt lgkmcnt(7)
	v_mfma_f32_32x32x16_bf16 v[34:49], v[102:105], v[194:197], v[34:49]
	s_waitcnt lgkmcnt(6)
	v_mfma_f32_32x32x16_bf16 v[18:33], v[106:109], v[194:197], v[18:33]
	s_waitcnt lgkmcnt(5)
	v_mfma_f32_32x32x16_bf16 v[2:17], v[110:113], v[194:197], v[2:17]
	s_waitcnt lgkmcnt(0)
	v_max_f32_e32 v255, v255, v255
	v_max_f32_e32 v98, v254, v255
	v_add_u32_e32 v255, s6, v232
	v_add_u32_e32 v239, 0xc800, v255
	v_add_u32_e32 v255, 0xea00, v255
	s_cmp_lg_u32 s4, 34
	s_waitcnt vmcnt(0)
	ds_write2_b64 v239, v[178:179], v[180:181] offset1:1
	ds_write2_b64 v255, v[182:183], v[184:185] offset1:1
	s_waitcnt vmcnt(0)
	s_waitcnt lgkmcnt(0)
	s_barrier
	v_mfma_f32_32x32x16_bf16 v[50:65], v[114:117], v[198:201], v[50:65]
	v_mfma_f32_32x32x16_bf16 v[34:49], v[118:121], v[198:201], v[34:49]
	v_mfma_f32_32x32x16_bf16 v[18:33], v[122:125], v[198:201], v[18:33]
	v_mfma_f32_32x32x16_bf16 v[2:17], v[126:129], v[198:201], v[2:17]
	s_cbranch_scc0 .LBB0_1845
.LBB0_1841:
	s_and_b32 s5, s4, 1
	s_xor_b32 s98, s5, 1
	s_mul_i32 s98, s98, 0x6400
	v_add_u32_e32 v233, s98, v229
	ds_read_b128 v[240:243], v233
	ds_read_b128 v[188:191], v233 offset:32
	ds_read_b128 v[114:117], v233 offset:12800
	ds_read_b128 v[192:195], v233 offset:12832
	s_mul_i32 s6, s5, 0x6400
	s_add_i32 s6, s6, 0
	s_add_i32 s7, s6, s42
	v_lshl_add_u64 v[100:101], s[30:31], 0, v[214:215]
	s_mov_b32 m0, s7
	s_and_b64 vcc, exec, s[2:3]
	global_load_lds_dwordx4 v[100:101], off
	v_lshl_add_u64 v[100:101], s[30:31], 0, v[216:217]
	s_add_i32 m0, s7, 0x2000
	s_nop 0
	global_load_lds_dwordx4 v[100:101], off
	v_lshl_add_u64 v[100:101], s[30:31], 0, v[218:219]
	s_add_i32 m0, s7, 0x4000
	s_nop 0
	global_load_lds_dwordx4 v[100:101], off
	s_cbranch_vccnz .LBB0_1843
	s_add_i32 m0, s6, 0x6000
	v_lshl_add_u64 v[100:101], s[30:31], 0, v[220:221]
	global_load_lds_dwordx4 v[100:101], off
